# v34 with non-temporal stores for the f32 output in the final phase
# speedup vs baseline: 1.0029x; 1.0029x over previous
.LBB0_169:
	global_load_dwordx2 v[44:45], v[34:35], off
	global_load_dwordx4 v[40:43], v[36:37], off offset:-2048
	global_load_dwordx4 v[56:59], v[36:37], off offset:-1024
	global_load_dwordx4 v[60:63], v[36:37], off
	global_load_dwordx4 v[64:67], v[36:37], off offset:1024
	s_movk_i32 s0, 0xf000
	v_add_co_u32_e32 v48, vcc, s0, v32
	v_add_u32_e32 v38, s8, v38
	s_nop 0
	v_addc_co_u32_e32 v49, vcc, -1, v33, vcc
	v_lshl_add_u64 v[34:35], v[34:35], 0, s[20:21]
	s_waitcnt vmcnt(4)
	v_ffbh_u32_e32 v39, v45
	v_min_u32_e32 v39, 32, v39
	v_lshlrev_b64 v[44:45], v39, v[44:45]
	v_min_u32_e32 v44, 1, v44
	v_or_b32_e32 v44, v45, v44
	v_cvt_f32_u32_e32 v44, v44
	v_sub_u32_e32 v39, 32, v39
	s_waitcnt vmcnt(3)
	v_lshlrev_b32_e32 v46, 16, v40
	v_and_b32_e32 v47, 0xffff0000, v40
	v_ldexp_f32 v39, v44, v39
	v_fmamk_f32 v39, v39, 0x30000000, v158
	v_mul_f32_e32 v44, 0x4b800000, v39
	v_cmp_gt_f32_e32 vcc, s37, v39
	v_lshlrev_b32_e32 v40, 16, v41
	v_and_b32_e32 v41, 0xffff0000, v41
	v_cndmask_b32_e32 v39, v39, v44, vcc
	v_rsq_f32_e32 v39, v39
	v_lshlrev_b32_e32 v50, 16, v42
	v_and_b32_e32 v51, 0xffff0000, v42
	v_lshlrev_b32_e32 v42, 16, v43
	v_mul_f32_e32 v44, 0x45800000, v39
	v_cndmask_b32_e32 v52, v39, v44, vcc
	v_and_b32_e32 v43, 0xffff0000, v43
	v_pk_mul_f32 v[44:45], v[52:53], v[46:47] op_sel_hi:[0,1]
	v_pk_mul_f32 v[46:47], v[52:53], v[40:41] op_sel_hi:[0,1]
	v_pk_mul_f32 v[40:41], v[52:53], v[50:51] op_sel_hi:[0,1]
	v_pk_mul_f32 v[42:43], v[52:53], v[42:43] op_sel_hi:[0,1]
	v_pk_mul_f32 v[46:47], v[30:31], v[46:47]
	v_pk_mul_f32 v[44:45], v[28:29], v[44:45]
	v_pk_mul_f32 v[42:43], v[26:27], v[42:43]
	v_pk_mul_f32 v[40:41], v[24:25], v[40:41]
	global_store_dwordx4 v[48:49], v[44:47], off offset:-2064 nt
	global_store_dwordx4 v[48:49], v[40:43], off offset:-2048 nt
	v_cmp_lt_i32_e32 vcc, s9, v38
	s_or_b64 s[14:15], vcc, s[14:15]
	s_waitcnt vmcnt(4)
	v_lshlrev_b32_e32 v44, 16, v56
	v_and_b32_e32 v45, 0xffff0000, v56
	v_lshlrev_b32_e32 v40, 16, v57
	v_and_b32_e32 v41, 0xffff0000, v57
	v_lshlrev_b32_e32 v46, 16, v58
	v_and_b32_e32 v47, 0xffff0000, v58
	v_lshlrev_b32_e32 v42, 16, v59
	v_and_b32_e32 v43, 0xffff0000, v59
	v_pk_mul_f32 v[44:45], v[52:53], v[44:45] op_sel_hi:[0,1]
	v_pk_mul_f32 v[50:51], v[52:53], v[40:41] op_sel_hi:[0,1]
	v_pk_mul_f32 v[40:41], v[52:53], v[46:47] op_sel_hi:[0,1]
	v_pk_mul_f32 v[42:43], v[52:53], v[42:43] op_sel_hi:[0,1]
	v_pk_mul_f32 v[46:47], v[22:23], v[50:51]
	v_pk_mul_f32 v[44:45], v[20:21], v[44:45]
	v_pk_mul_f32 v[42:43], v[18:19], v[42:43]
	v_pk_mul_f32 v[40:41], v[16:17], v[40:41]
	global_store_dwordx4 v[48:49], v[44:47], off offset:-16 nt
	global_store_dwordx4 v[32:33], v[40:43], off offset:-4096 nt
	s_waitcnt vmcnt(5)
	v_lshlrev_b32_e32 v44, 16, v60
	v_and_b32_e32 v45, 0xffff0000, v60
	v_lshlrev_b32_e32 v40, 16, v61
	v_and_b32_e32 v41, 0xffff0000, v61
	v_lshlrev_b32_e32 v46, 16, v62
	v_and_b32_e32 v47, 0xffff0000, v62
	v_lshlrev_b32_e32 v42, 16, v63
	v_and_b32_e32 v43, 0xffff0000, v63
	v_pk_mul_f32 v[44:45], v[52:53], v[44:45] op_sel_hi:[0,1]
	v_pk_mul_f32 v[48:49], v[52:53], v[40:41] op_sel_hi:[0,1]
	v_pk_mul_f32 v[40:41], v[52:53], v[46:47] op_sel_hi:[0,1]
	v_pk_mul_f32 v[42:43], v[52:53], v[42:43] op_sel_hi:[0,1]
	v_pk_mul_f32 v[46:47], v[6:7], v[48:49]
	v_pk_mul_f32 v[44:45], v[4:5], v[44:45]
	v_pk_mul_f32 v[42:43], v[14:15], v[42:43]
	v_pk_mul_f32 v[40:41], v[12:13], v[40:41]
	global_store_dwordx4 v[32:33], v[44:47], off offset:-2064 nt
	global_store_dwordx4 v[32:33], v[40:43], off offset:-2048 nt
	v_lshl_add_u64 v[36:37], v[36:37], 0, s[22:23]
	s_waitcnt vmcnt(6)
	v_lshlrev_b32_e32 v44, 16, v64
	v_and_b32_e32 v45, 0xffff0000, v64
	v_lshlrev_b32_e32 v40, 16, v65
	v_and_b32_e32 v41, 0xffff0000, v65
	v_lshlrev_b32_e32 v46, 16, v66
	v_and_b32_e32 v47, 0xffff0000, v66
	v_lshlrev_b32_e32 v42, 16, v67
	v_and_b32_e32 v43, 0xffff0000, v67
	v_pk_mul_f32 v[44:45], v[52:53], v[44:45] op_sel_hi:[0,1]
	v_pk_mul_f32 v[48:49], v[52:53], v[40:41] op_sel_hi:[0,1]
	v_pk_mul_f32 v[40:41], v[52:53], v[46:47] op_sel_hi:[0,1]
	v_pk_mul_f32 v[42:43], v[52:53], v[42:43] op_sel_hi:[0,1]
	v_pk_mul_f32 v[46:47], v[10:11], v[48:49]
	v_pk_mul_f32 v[44:45], v[8:9], v[44:45]
	v_pk_mul_f32 v[42:43], v[2:3], v[42:43]
	v_pk_mul_f32 v[40:41], v[0:1], v[40:41]
	global_store_dwordx4 v[32:33], v[44:47], off offset:-16 nt
	global_store_dwordx4 v[32:33], v[40:43], off nt
	v_lshl_add_u64 v[32:33], v[32:33], 0, s[18:19]
	s_andn2_b64 exec, exec, s[14:15]
	s_cbranch_execnz .LBB0_169
